# XCD-group start skew (bid&7 x ~1.5us) in the two FFN gate-up GEMM phases, to de-synchronise the per-tile output store bursts
# baseline (speedup 1.0000x reference)
;     __device__ bool next(int i, Unit& u) const {
;         const long L = (long)i * G + c; if (L >= nwg) return false;
;         int wgid = (int)L; { const int q = nwg / NXCD, r = nwg % NXCD, xcd = wgid % NXCD, off = wgid / NXCD; wgid = (xcd < r ? xcd * (q + 1) : r * (q + 1) + (xcd - r) * q) + off; }
;         const int nig = WGM * nN, gid = wgid / nig, fm = gid * WGM, gsz = (nM - fm) < WGM ? (nM - fm) : WGM;
;         u.pm = fm + ((wgid % nig) % gsz); u.pn = (wgid % nig) / gsz; return true;
;     }
; template <class Epi, bool ALIGN_EPI, int K, int LDA, int LDB>
; __device__ __forceinline__ void gemm_phase(LAS unsigned char* lds, const int wid, const Gemm g, const StaticOrder& S, const Epi& E) {
;     const int lane = lane_id_(), tid = wid * 64 + lane, wr = wid >> 2, wc = wid & 3, fr = lane & 15, fq = lane >> 4;
;     constexpr int nt = K / BK;
;     unsigned voffA[2], voffB[2];
; #pragma unroll
;     for (int i = 0; i < 2; ++i) { int R, C; stage_rc(tid * 16 + i * 8192, R, C); const int Rb = Epi::PERM ? ((R & ~31) + perm32(R & 31)) : R;
;         voffA[i] = (unsigned)(R * LDA + C) * 2u; voffB[i] = (unsigned)(Rb * LDB + C) * 2u; }
;     constexpr size_t kstep = (size_t)(BK * 2);
;     constexpr size_t hA = (size_t)HALF * LDA * 2, hB = (size_t)HALF * LDB * 2;
;     constexpr size_t tA = 2 * hA, tB = 2 * hB;
;     const unsigned ldsw = (unsigned)wid * 1024u;
;     const int aoff = lds_byte(wr * 64 + fr, fq * 8), boff = lds_byte(wc * 32 + fr, fq * 8);
;     ...
;     Unit cur, nxt; int ui = 0;
;     if (!S.next(0, cur)) return;
;     f32x4 acc[2][2][4][2];
; #pragma unroll
;     for (int a = 0; a < 2; ++a)
; #pragma unroll
;         for (int b = 0; b < 2; ++b)
; #pragma unroll
;             for (int m = 0; m < 4; ++m)
; #pragma unroll
;                 for (int n = 0; n < 2; ++n) acc[a][b][m][n] = (f32x4){0.f, 0.f, 0.f, 0.f};
;     bf16x8 At[4][2], B0[2][2], B1[2][2];
;     const char* cA = (const char*)g.A + (size_t)cur.pm * tA; const char* cB = (const char*)g.Bt + (size_t)cur.pn * tB;
;     PG8_STAGE(PG8_SB(0, 0), cB, voffB); PG8_STAGE(PG8_SB(0, 1), cB + hB, voffB); PG8_STAGE(PG8_SA(0, 0), cA, voffA); PG8_STAGE(PG8_SA(0, 1), cA + hA, voffA);
;     if (wr == 1) PG8_BAR;
;     PG8_WAIT_V(2); PG8_BAR;
;     PG8_STAGE(PG8_SB(1, 0), cB + kstep, voffB); PG8_STAGE(PG8_SA(1, 0), cA + kstep, voffA); PG8_STAGE(PG8_SB(1, 1), cB + hB + kstep, voffB);
.LBB0_1042:
	s_cmp_lt_i32 s84, 9
	s_cselect_b64 s[0:1], -1, 0
	s_cmp_gt_i32 s85, 8
	s_cselect_b64 s[4:5], -1, 0
	s_and_b64 s[0:1], s[0:1], s[4:5]
	s_andn2_b64 vcc, exec, s[0:1]
	s_cbranch_vccnz .LBB0_1115
	s_and_b32 s98, s2, 7
	s_cmp_eq_u32 s98, 0
	s_cbranch_scc1 .Lskew_p8_done
.Lskew_p8_loop:
	s_sleep 48
	s_sub_u32 s98, s98, 1
	s_cmp_lg_u32 s98, 0
	s_cbranch_scc1 .Lskew_p8_loop
.Lskew_p8_done:
	s_mov_b64 s[0:1], s[88:89]
	s_cmpk_lt_i32 s2, 0x1600
	v_mbcnt_lo_u32_b32 v8, -1, 0
	v_mbcnt_hi_u32_b32 v8, -1, v8
	s_cbranch_scc0 .LBB0_1059
	s_add_u32 s0, s46, 0x1800000
	s_addc_u32 s1, s47, 0
	s_lshr_b32 s5, s86, 8
	s_lshl_b32 s3, s50, 10
	s_cmp_eq_u32 s5, 1
	s_cselect_b64 s[6:7], -1, 0
	s_ashr_i32 s28, s2, 31
	s_lshr_b32 s4, s28, 29
	s_add_i32 s4, s2, s4
	s_ashr_i32 s8, s4, 3
	s_and_b32 s4, s4, -8
	s_sub_i32 s4, s2, s4
	s_cmp_lt_i32 s4, 0
	s_movk_i32 s29, 0x2c1
	s_cselect_b32 s9, s29, 0x2c0
	s_mul_i32 s4, s4, s9
	s_add_i32 s4, s4, s8
	s_mul_hi_i32 s8, s4, 0x2e8ba2e9
	s_lshr_b32 s9, s8, 31
	s_ashr_i32 s8, s8, 5
	s_add_i32 s8, s8, s9
	s_lshl_b32 s9, s8, 3
	s_mulk_i32 s8, 0xb0
	s_waitcnt lgkmcnt(0)
	v_lshl_add_u32 v0, v8, 4, s3
	s_sub_i32 s8, s4, s8
	v_add_u32_e32 v1, 0x2000, v0
	s_sext_i32_i16 s4, s8
	v_ashrrev_i32_e32 v2, 31, v1
	s_bfe_u32 s4, s4, 0x3001c
	v_lshrrev_b32_e32 v2, 22, v2
	s_add_i32 s10, s8, s4
	v_add_u32_e32 v2, v1, v2
	s_sext_i32_i16 s4, s10
	s_and_b32 s10, s10, 0xfff8
	v_ashrrev_i32_e32 v9, 10, v2
	s_sub_i32 s8, s8, s10
	v_mul_i32_i24_e32 v2, 0x400, v9
	s_sext_i32_i16 s8, s8
	v_sub_u32_e32 v1, v1, v2
	s_lshr_b32 s4, s4, 3
	s_add_i32 s20, s9, s8
	v_lshrrev_b32_e32 v2, 4, v1
	s_ashr_i32 s21, s20, 31
	s_bfe_i64 s[10:11], s[4:5], 0x100000
	v_bitop3_b32 v1, v2, v1, 32 bitop3:0x6c
	s_lshl_b64 s[8:9], s[20:21], 19
	s_lshl_b64 s[10:11], s[10:11], 19
	v_ashrrev_i32_e32 v2, 31, v1
	s_add_u32 s24, s0, s10
	v_lshrrev_b32_e32 v2, 26, v2
	s_addc_u32 s25, s1, s11
	s_add_i32 s21, s3, 0
	v_add_u32_e32 v2, v1, v2
	s_add_i32 m0, s21, 0x10000
	s_add_i32 s12, s21, 0x12000
	v_ashrrev_i32_e32 v10, 6, v2
	v_lshlrev_b32_e32 v3, 3, v9
	v_and_b32_e32 v2, 0xffc0, v2
	s_add_u32 s10, s24, 0x40000
	v_and_b32_e32 v3, -16, v3
	v_sub_u32_e32 v1, v1, v2
	s_addc_u32 s11, s25, 0
	s_add_i32 s13, s21, 0x14000
	s_add_i32 s14, s21, 0x16000
	v_readlane_b32 s15, v254, 0
	v_add_u32_e32 v3, v10, v3
	v_lshrrev_b16_e32 v2, 7, v1
	s_add_u32 s22, s15, s8
	v_and_b32_e32 v4, 3, v10
	s_mov_b32 s15, 0x1fffe0
	v_lshrrev_b32_e32 v5, 2, v3
	v_lshlrev_b32_e32 v6, 1, v3
	v_and_b32_e32 v2, 1, v2
	v_and_or_b32 v4, v3, s15, v4
	v_and_b32_e32 v5, 4, v5
	v_and_b32_e32 v6, 24, v6
	v_add_u16_e32 v1, v1, v2
	v_mov_b32_e32 v2, 1
	v_or3_b32 v4, v4, v5, v6
	v_lshlrev_b32_e32 v5, 5, v9
	v_ashrrev_i16_sdwa v1, v2, sext(v1) dst_sel:DWORD dst_unused:UNUSED_PAD src0_sel:DWORD src1_sel:BYTE_0
	v_and_b32_e32 v5, 32, v5
	v_bfe_i32 v11, v1, 0, 16
	v_add_lshl_u32 v1, v5, v11, 1
	v_lshl_add_u32 v128, v4, 11, v1
	v_lshl_add_u32 v130, v3, 11, v1
	v_ashrrev_i32_e32 v1, 31, v0
	v_lshrrev_b32_e32 v1, 22, v1
	v_add_u32_e32 v1, v0, v1
	v_ashrrev_i32_e32 v12, 10, v1
	v_mul_i32_i24_e32 v1, 0x400, v12
	v_sub_u32_e32 v0, v0, v1
	v_lshrrev_b32_e32 v1, 4, v0
	v_bitop3_b32 v0, v1, v0, 32 bitop3:0x6c
	v_ashrrev_i32_e32 v1, 31, v0
	v_lshrrev_b32_e32 v1, 26, v1
	v_add_u32_e32 v1, v0, v1
	v_lshlrev_b32_e32 v3, 3, v12
	v_ashrrev_i32_e32 v13, 6, v1
	v_and_b32_e32 v3, -16, v3
	v_add_u32_e32 v3, v13, v3
	v_and_b32_e32 v4, 3, v13
	v_lshrrev_b32_e32 v5, 2, v3
	v_lshlrev_b32_e32 v6, 1, v3
	v_and_b32_e32 v1, 0xc0, v1
	v_and_or_b32 v4, v3, s15, v4
	v_and_b32_e32 v5, 4, v5
	v_and_b32_e32 v6, 24, v6
	v_sub_u32_e32 v0, v0, v1
	v_or3_b32 v4, v4, v5, v6
	v_lshlrev_b32_e32 v5, 5, v12
	v_ashrrev_i16_sdwa v0, v2, sext(v0) dst_sel:DWORD dst_unused:UNUSED_PAD src0_sel:DWORD src1_sel:BYTE_0
	v_and_b32_e32 v5, 32, v5
	v_bfe_i32 v14, v0, 0, 16
	v_add_lshl_u32 v0, v5, v14, 1
	v_lshl_add_u32 v132, v4, 11, v0
	global_load_lds_dwordx4 v132, s[24:25]
	s_mov_b32 m0, s12
	v_readlane_b32 s8, v254, 1
	global_load_lds_dwordx4 v128, s[24:25]
	s_mov_b32 m0, s13
	s_addc_u32 s23, s8, s9
	s_add_i32 s30, s21, 0x2000
	global_load_lds_dwordx4 v132, s[10:11]
	s_mov_b32 m0, s14
	s_add_u32 s8, s22, 0x40000
	v_lshl_add_u32 v134, v3, 11, v0
	global_load_lds_dwordx4 v128, s[10:11]
	s_mov_b32 m0, s21
	s_addc_u32 s9, s23, 0
	s_add_i32 s31, s21, 0x4000
	global_load_lds_dwordx4 v134, s[22:23]
	s_mov_b32 m0, s30
	s_add_i32 s33, s21, 0x6000
	global_load_lds_dwordx4 v130, s[22:23]
	s_mov_b32 m0, s31
	v_mov_b32_e32 v133, 0
	global_load_lds_dwordx4 v134, s[8:9]
	s_mov_b32 m0, s33
	v_mov_b32_e32 v129, v133
	global_load_lds_dwordx4 v130, s[8:9]
	v_mov_b32_e32 v135, v133
	v_mov_b32_e32 v131, v133
	s_mov_b32 s34, 0
	s_cmp_lg_u32 s5, 1
	v_lshl_add_u64 v[6:7], s[24:25], 0, v[132:133]
	v_lshl_add_u64 v[4:5], s[24:25], 0, v[128:129]
	v_lshl_add_u64 v[2:3], s[22:23], 0, v[134:135]
	v_lshl_add_u64 v[0:1], s[22:23], 0, v[130:131]
	s_cbranch_scc1 .LBB0_1046
	s_barrier

; #define PHASE_BEGIN if (lo <= ph && ph < hi) { { unsigned long long ta_ = (unsigned long long)__builtin_amdgcn_kernarg_segment_ptr(); asm volatile("" : "+s"(ta_)); F.in = (const __attribute__((address_space(4))) unsigned long long*)ta_; }
; #define PHASE_END   if (ph + 1 < hi) { if (ph == 0) grid.sync(); else for (int rb = 0; rb < REP_BAR; ++rb) grid_bar(F, (++nbar) * (unsigned)F.G); } } ++ph;
; __global__ void __launch_bounds__(NTHREADS) fwd_mega(Args args) {
;     ...
;     PHASE_BEGIN { pg8::Gemm g{HB, (const bf16_t*)(ws + WS_WGU) + (size_t)5632 * 1024}; SO.init(T, 2 * FF, F.G, F.bid);
;         pg8::EpiSwiglu E{BIG}; for (int rep = 0; rep < REP_GEMM; ++rep) pg8::gemm_phase<pg8::EpiSwiglu, true, 1024, 1024, 1024>(F.lds, F.wid, g, SO, E); } PHASE_END
.LBB0_1602:
	s_cmp_lt_i32 s84, 16
	s_cselect_b64 s[0:1], -1, 0
	s_cmp_gt_i32 s85, 15
	s_cselect_b64 s[4:5], -1, 0
	s_and_b64 s[0:1], s[0:1], s[4:5]
	s_andn2_b64 vcc, exec, s[0:1]
	s_cbranch_vccnz .LBB0_1675
	s_and_b32 s98, s2, 7
	s_cmp_eq_u32 s98, 0
	s_cbranch_scc1 .Lskew_p15_done

;     __device__ bool next(int i, Unit& u) const {
;         const long L = (long)i * G + c; if (L >= nwg) return false;
;         int wgid = (int)L; { const int q = nwg / NXCD, r = nwg % NXCD, xcd = wgid % NXCD, off = wgid / NXCD; wgid = (xcd < r ? xcd * (q + 1) : r * (q + 1) + (xcd - r) * q) + off; }
;         const int nig = WGM * nN, gid = wgid / nig, fm = gid * WGM, gsz = (nM - fm) < WGM ? (nM - fm) : WGM;
;         u.pm = fm + ((wgid % nig) % gsz); u.pn = (wgid % nig) / gsz; return true;
;     }
; template <class Epi, bool ALIGN_EPI, int K, int LDA, int LDB>
; __device__ __forceinline__ void gemm_phase(LAS unsigned char* lds, const int wid, const Gemm g, const StaticOrder& S, const Epi& E) {
;     const int lane = lane_id_(), tid = wid * 64 + lane, wr = wid >> 2, wc = wid & 3, fr = lane & 15, fq = lane >> 4;
;     constexpr int nt = K / BK;
;     unsigned voffA[2], voffB[2];
; #pragma unroll
;     for (int i = 0; i < 2; ++i) { int R, C; stage_rc(tid * 16 + i * 8192, R, C); const int Rb = Epi::PERM ? ((R & ~31) + perm32(R & 31)) : R;
;         voffA[i] = (unsigned)(R * LDA + C) * 2u; voffB[i] = (unsigned)(Rb * LDB + C) * 2u; }
;     constexpr size_t kstep = (size_t)(BK * 2);
;     constexpr size_t hA = (size_t)HALF * LDA * 2, hB = (size_t)HALF * LDB * 2;
;     constexpr size_t tA = 2 * hA, tB = 2 * hB;
;     const unsigned ldsw = (unsigned)wid * 1024u;
;     const int aoff = lds_byte(wr * 64 + fr, fq * 8), boff = lds_byte(wc * 32 + fr, fq * 8);
;     ...
;     Unit cur, nxt; int ui = 0;
;     if (!S.next(0, cur)) return;
;     f32x4 acc[2][2][4][2];
; #pragma unroll
;     for (int a = 0; a < 2; ++a)
; #pragma unroll
;         for (int b = 0; b < 2; ++b)
; #pragma unroll
;             for (int m = 0; m < 4; ++m)
; #pragma unroll
;                 for (int n = 0; n < 2; ++n) acc[a][b][m][n] = (f32x4){0.f, 0.f, 0.f, 0.f};
;     bf16x8 At[4][2], B0[2][2], B1[2][2];
;     const char* cA = (const char*)g.A + (size_t)cur.pm * tA; const char* cB = (const char*)g.Bt + (size_t)cur.pn * tB;
;     PG8_STAGE(PG8_SB(0, 0), cB, voffB); PG8_STAGE(PG8_SB(0, 1), cB + hB, voffB); PG8_STAGE(PG8_SA(0, 0), cA, voffA); PG8_STAGE(PG8_SA(0, 1), cA + hA, voffA);
;     if (wr == 1) PG8_BAR;
;     PG8_WAIT_V(2); PG8_BAR;
;     PG8_STAGE(PG8_SB(1, 0), cB + kstep, voffB); PG8_STAGE(PG8_SA(1, 0), cA + kstep, voffA); PG8_STAGE(PG8_SB(1, 1), cB + hB + kstep, voffB);
.Lskew_p15_done:
	s_mov_b64 s[0:1], s[88:89]
	s_cmpk_lt_i32 s2, 0x1600
	v_mbcnt_lo_u32_b32 v8, -1, 0
	v_mbcnt_hi_u32_b32 v8, -1, v8
	s_cbranch_scc0 .LBB0_1619
	s_add_u32 s0, s46, 0x2300000
	s_addc_u32 s1, s47, 0
	s_lshr_b32 s5, s86, 8
	s_lshl_b32 s3, s50, 10
	s_cmp_eq_u32 s5, 1
	s_cselect_b64 s[6:7], -1, 0
	s_ashr_i32 s28, s2, 31
	s_lshr_b32 s4, s28, 29
	s_add_i32 s4, s2, s4
	s_ashr_i32 s8, s4, 3
	s_and_b32 s4, s4, -8
	s_sub_i32 s4, s2, s4
	s_cmp_lt_i32 s4, 0
	s_movk_i32 s29, 0x2c1
	s_cselect_b32 s9, s29, 0x2c0
	s_mul_i32 s4, s4, s9
	s_add_i32 s4, s4, s8
	s_mul_hi_i32 s8, s4, 0x2e8ba2e9
	s_lshr_b32 s9, s8, 31
	s_ashr_i32 s8, s8, 5
	s_add_i32 s8, s8, s9
	s_lshl_b32 s9, s8, 3
	s_mulk_i32 s8, 0xb0
	s_waitcnt lgkmcnt(0)
	v_lshl_add_u32 v0, v8, 4, s3
	s_sub_i32 s8, s4, s8
	v_add_u32_e32 v1, 0x2000, v0
	s_sext_i32_i16 s4, s8
	v_ashrrev_i32_e32 v2, 31, v1
	s_bfe_u32 s4, s4, 0x3001c
	v_lshrrev_b32_e32 v2, 22, v2
	s_add_i32 s10, s8, s4
	v_add_u32_e32 v2, v1, v2
	s_sext_i32_i16 s4, s10
	s_and_b32 s10, s10, 0xfff8
	v_ashrrev_i32_e32 v9, 10, v2
	s_sub_i32 s8, s8, s10
	v_mul_i32_i24_e32 v2, 0x400, v9
	s_sext_i32_i16 s8, s8
	v_sub_u32_e32 v1, v1, v2
	s_lshr_b32 s4, s4, 3
	s_add_i32 s20, s9, s8
	v_lshrrev_b32_e32 v2, 4, v1
	s_ashr_i32 s21, s20, 31
	s_bfe_i64 s[10:11], s[4:5], 0x100000
	v_bitop3_b32 v1, v2, v1, 32 bitop3:0x6c
	s_lshl_b64 s[8:9], s[20:21], 19
	s_lshl_b64 s[10:11], s[10:11], 19
	v_ashrrev_i32_e32 v2, 31, v1
	s_add_u32 s24, s0, s10
	v_lshrrev_b32_e32 v2, 26, v2
	s_addc_u32 s25, s1, s11
	s_add_i32 s21, s3, 0
	v_add_u32_e32 v2, v1, v2
	s_add_i32 m0, s21, 0x10000
	s_add_i32 s12, s21, 0x12000
	v_ashrrev_i32_e32 v10, 6, v2
	v_lshlrev_b32_e32 v3, 3, v9
	v_and_b32_e32 v2, 0xffc0, v2
	s_add_u32 s10, s24, 0x40000
	v_and_b32_e32 v3, -16, v3
	v_sub_u32_e32 v1, v1, v2
	s_addc_u32 s11, s25, 0
	s_add_i32 s13, s21, 0x14000
	s_add_i32 s14, s21, 0x16000
	v_readlane_b32 s15, v254, 0
	v_add_u32_e32 v3, v10, v3
	v_lshrrev_b16_e32 v2, 7, v1
	s_add_u32 s22, s15, s8
	v_and_b32_e32 v4, 3, v10
	s_mov_b32 s15, 0x1fffe0
	v_lshrrev_b32_e32 v5, 2, v3
	v_lshlrev_b32_e32 v6, 1, v3
	v_and_b32_e32 v2, 1, v2
	v_and_or_b32 v4, v3, s15, v4
	v_and_b32_e32 v5, 4, v5
	v_and_b32_e32 v6, 24, v6
	v_add_u16_e32 v1, v1, v2
	v_mov_b32_e32 v2, 1
	v_or3_b32 v4, v4, v5, v6
	v_lshlrev_b32_e32 v5, 5, v9
	v_ashrrev_i16_sdwa v1, v2, sext(v1) dst_sel:DWORD dst_unused:UNUSED_PAD src0_sel:DWORD src1_sel:BYTE_0
	v_and_b32_e32 v5, 32, v5
	v_bfe_i32 v11, v1, 0, 16
	v_add_lshl_u32 v1, v5, v11, 1
	v_lshl_add_u32 v128, v4, 11, v1
	v_lshl_add_u32 v130, v3, 11, v1
	v_ashrrev_i32_e32 v1, 31, v0
	v_lshrrev_b32_e32 v1, 22, v1
	v_add_u32_e32 v1, v0, v1
	v_ashrrev_i32_e32 v12, 10, v1
	v_mul_i32_i24_e32 v1, 0x400, v12
	v_sub_u32_e32 v0, v0, v1
	v_lshrrev_b32_e32 v1, 4, v0
	v_bitop3_b32 v0, v1, v0, 32 bitop3:0x6c
	v_ashrrev_i32_e32 v1, 31, v0
	v_lshrrev_b32_e32 v1, 26, v1
	v_add_u32_e32 v1, v0, v1
	v_lshlrev_b32_e32 v3, 3, v12
	v_ashrrev_i32_e32 v13, 6, v1
	v_and_b32_e32 v3, -16, v3
	v_add_u32_e32 v3, v13, v3
	v_and_b32_e32 v4, 3, v13
	v_lshrrev_b32_e32 v5, 2, v3
	v_lshlrev_b32_e32 v6, 1, v3
	v_and_b32_e32 v1, 0xc0, v1
	v_and_or_b32 v4, v3, s15, v4
	v_and_b32_e32 v5, 4, v5
	v_and_b32_e32 v6, 24, v6
	v_sub_u32_e32 v0, v0, v1
	v_or3_b32 v4, v4, v5, v6
	v_lshlrev_b32_e32 v5, 5, v12
	v_ashrrev_i16_sdwa v0, v2, sext(v0) dst_sel:DWORD dst_unused:UNUSED_PAD src0_sel:DWORD src1_sel:BYTE_0
	v_and_b32_e32 v5, 32, v5
	v_bfe_i32 v14, v0, 0, 16
	v_add_lshl_u32 v0, v5, v14, 1
	v_lshl_add_u32 v132, v4, 11, v0
	global_load_lds_dwordx4 v132, s[24:25]
	s_mov_b32 m0, s12
	v_readlane_b32 s8, v254, 1
	global_load_lds_dwordx4 v128, s[24:25]
	s_mov_b32 m0, s13
	s_addc_u32 s23, s8, s9
	s_add_i32 s30, s21, 0x2000
	global_load_lds_dwordx4 v132, s[10:11]
	s_mov_b32 m0, s14
	s_add_u32 s8, s22, 0x40000
	v_lshl_add_u32 v134, v3, 11, v0
	global_load_lds_dwordx4 v128, s[10:11]
	s_mov_b32 m0, s21
	s_addc_u32 s9, s23, 0
	s_add_i32 s31, s21, 0x4000
	global_load_lds_dwordx4 v134, s[22:23]
	s_mov_b32 m0, s30
	s_add_i32 s33, s21, 0x6000
	global_load_lds_dwordx4 v130, s[22:23]
	s_mov_b32 m0, s31
	v_mov_b32_e32 v133, 0
	global_load_lds_dwordx4 v134, s[8:9]
	s_mov_b32 m0, s33
	v_mov_b32_e32 v129, v133
	global_load_lds_dwordx4 v130, s[8:9]
	v_mov_b32_e32 v135, v133
	v_mov_b32_e32 v131, v133
	s_mov_b32 s34, 0
	s_cmp_lg_u32 s5, 1
	v_lshl_add_u64 v[6:7], s[24:25], 0, v[132:133]
	v_lshl_add_u64 v[4:5], s[24:25], 0, v[128:129]
	v_lshl_add_u64 v[2:3], s[22:23], 0, v[134:135]
	v_lshl_add_u64 v[0:1], s[22:23], 0, v[130:131]
	s_cbranch_scc1 .LBB0_1606
	s_barrier
